# v14: v13 + box filter divisions by the window count as refined-reciprocal multiply with exact-residual correction (bit-identical quotients), replacing 128 IEEE division sequences per workgroup
# speedup vs baseline: 1.0509x; 1.0037x over previous
; #define LAS __attribute__((address_space(3)))
; __device__ void boxfilter_unit(const Params& p, LAS unsigned char* lds, int u) {
;     ...
;     for (int i = 0; i < 4; ++i) { const int tok = tid + 512 * i; const int r = tok >> 6, c = tok & 63; const int lo = max(r - hw, 0), hi = min(r + hw, 32);
;         f32x4 s0 = (f32x4){0.f, 0.f, 0.f, 0.f}, s1 = s0;
;         for (int rr = lo; rr < hi; ++rr) { s0 += *(const LAS f32x4*)(X + (rr * 64 + c) * 8); s1 += *(const LAS f32x4*)(X + (rr * 64 + c) * 8 + 4); }
;         const float cnt = (float)(hi - lo);
;         *(LAS f32x4*)(Y + tok * 8) = s0 / cnt; *(LAS f32x4*)(Y + tok * 8 + 4) = s1 / cnt; }
.LBB0_406:
	s_or_b64 exec, exec, s[0:1]
	v_sub_u32_e32 v21, v22, v21
	v_cvt_f32_i32_e32 v21, v21
	v_rcp_f32_e32 v106, v21
	s_nop 0
	v_fma_f32 v107, -v21, v106, 1.0
	v_fmac_f32_e32 v106, v107, v106
	v_fma_f32 v107, -v21, v106, 1.0
	v_fmac_f32_e32 v106, v107, v106
	v_mul_f32_e32 v108, v13, v106
	v_fma_f32 v107, -v21, v108, v13
	v_fma_f32 v25, v107, v106, v108
	v_mul_f32_e32 v108, v12, v106
	v_fma_f32 v107, -v21, v108, v12
	v_fma_f32 v24, v107, v106, v108
	v_mul_f32_e32 v108, v15, v106
	v_fma_f32 v107, -v21, v108, v15
	v_fma_f32 v23, v107, v106, v108
	v_mul_f32_e32 v108, v14, v106
	v_fma_f32 v107, -v21, v108, v14
	v_fma_f32 v22, v107, v106, v108
	v_add_u32_e32 v12, 0x10000, v19
	ds_write_b128 v12, v[22:25]
	v_mul_f32_e32 v108, v11, v106
	v_fma_f32 v107, -v21, v108, v11
	v_fma_f32 v11, v107, v106, v108
	v_mul_f32_e32 v108, v10, v106
	v_fma_f32 v107, -v21, v108, v10
	v_fma_f32 v10, v107, v106, v108
	v_mul_f32_e32 v108, v9, v106
	v_fma_f32 v107, -v21, v108, v9
	v_fma_f32 v9, v107, v106, v108
	v_mul_f32_e32 v108, v8, v106
	v_fma_f32 v107, -v21, v108, v8
	v_fma_f32 v8, v107, v106, v108
	ds_write_b128 v12, v[8:11] offset:16
	v_ashrrev_i32_e32 v8, 6, v4
	v_subrev_u32_e32 v9, s6, v8
	v_add_u32_e32 v8, s6, v8
	v_max_i32_e32 v21, 0, v9
	v_min_i32_e32 v22, 32, v8
	v_mov_b32_e32 v15, 0
	v_cmp_gt_i32_e32 vcc, v22, v21
	v_mov_b32_e32 v14, v15
	v_mov_b32_e32 v13, v15
	v_mov_b32_e32 v12, v15
	v_mov_b32_e32 v11, v15
	v_mov_b32_e32 v10, v15
	v_mov_b32_e32 v9, v15
	v_mov_b32_e32 v8, v15
	s_and_saveexec_b64 s[0:1], vcc
	s_cbranch_execz .LBB0_410
	v_lshlrev_b32_e32 v8, 5, v20
	v_lshl_or_b32 v8, v21, 11, v8
	v_mov_b32_e32 v12, 0
	v_add_u32_e32 v23, 0, v8
	s_mov_b64 s[4:5], 0
	v_mov_b32_e32 v24, v21
	v_mov_b32_e32 v13, v12
	v_mov_b32_e32 v14, v12
	v_mov_b32_e32 v15, v12
	v_mov_b32_e32 v8, v12
	v_mov_b32_e32 v9, v12
	v_mov_b32_e32 v10, v12
	v_mov_b32_e32 v11, v12

; #define LAS __attribute__((address_space(3)))
; __device__ void boxfilter_unit(const Params& p, LAS unsigned char* lds, int u) {
;     ...
;     for (int i = 0; i < 4; ++i) { const int tok = tid + 512 * i; const int r = tok >> 6, c = tok & 63; const int lo = max(r - hw, 0), hi = min(r + hw, 32);
;         f32x4 s0 = (f32x4){0.f, 0.f, 0.f, 0.f}, s1 = s0;
;         for (int rr = lo; rr < hi; ++rr) { s0 += *(const LAS f32x4*)(X + (rr * 64 + c) * 8); s1 += *(const LAS f32x4*)(X + (rr * 64 + c) * 8 + 4); }
;         const float cnt = (float)(hi - lo);
;         *(LAS f32x4*)(Y + tok * 8) = s0 / cnt; *(LAS f32x4*)(Y + tok * 8 + 4) = s1 / cnt; }
.LBB0_410:
	s_or_b64 exec, exec, s[0:1]
	v_sub_u32_e32 v21, v22, v21
	v_cvt_f32_i32_e32 v21, v21
	v_rcp_f32_e32 v106, v21
	s_nop 0
	v_fma_f32 v107, -v21, v106, 1.0
	v_fmac_f32_e32 v106, v107, v106
	v_fma_f32 v107, -v21, v106, 1.0
	v_fmac_f32_e32 v106, v107, v106
	v_mul_f32_e32 v108, v15, v106
	v_fma_f32 v107, -v21, v108, v15
	v_fma_f32 v15, v107, v106, v108
	v_mul_f32_e32 v108, v14, v106
	v_fma_f32 v107, -v21, v108, v14
	v_fma_f32 v14, v107, v106, v108
	v_mul_f32_e32 v108, v13, v106
	v_fma_f32 v107, -v21, v108, v13
	v_fma_f32 v13, v107, v106, v108
	v_mul_f32_e32 v108, v12, v106
	v_fma_f32 v107, -v21, v108, v12
	v_fma_f32 v12, v107, v106, v108
	v_add_u32_e32 v22, 0x10000, v18
	ds_write_b128 v22, v[12:15]
	v_mul_f32_e32 v108, v11, v106
	v_fma_f32 v107, -v21, v108, v11
	v_fma_f32 v11, v107, v106, v108
	v_mul_f32_e32 v108, v10, v106
	v_fma_f32 v107, -v21, v108, v10
	v_fma_f32 v10, v107, v106, v108
	v_mul_f32_e32 v108, v9, v106
	v_fma_f32 v107, -v21, v108, v9
	v_fma_f32 v9, v107, v106, v108
	v_mul_f32_e32 v108, v8, v106
	v_fma_f32 v107, -v21, v108, v8
	v_fma_f32 v8, v107, v106, v108
	ds_write_b128 v22, v[8:11] offset:16
	v_ashrrev_i32_e32 v8, 6, v2
	v_subrev_u32_e32 v9, s6, v8
	v_add_u32_e32 v8, s6, v8
	v_max_i32_e32 v21, 0, v9
	v_min_i32_e32 v22, 32, v8
	v_mov_b32_e32 v15, 0
	v_cmp_gt_i32_e32 vcc, v22, v21
	v_mov_b32_e32 v14, v15
	v_mov_b32_e32 v13, v15
	v_mov_b32_e32 v12, v15
	v_mov_b32_e32 v11, v15
	v_mov_b32_e32 v10, v15
	v_mov_b32_e32 v9, v15
	v_mov_b32_e32 v8, v15
	s_and_saveexec_b64 s[0:1], vcc
	s_cbranch_execz .LBB0_414
	v_lshlrev_b32_e32 v8, 5, v20
	v_lshl_or_b32 v8, v21, 11, v8
	v_mov_b32_e32 v12, 0
	v_add_u32_e32 v23, 0, v8
	s_mov_b64 s[4:5], 0
	v_mov_b32_e32 v24, v21
	v_mov_b32_e32 v13, v12
	v_mov_b32_e32 v14, v12
	v_mov_b32_e32 v15, v12
	v_mov_b32_e32 v8, v12
	v_mov_b32_e32 v9, v12
	v_mov_b32_e32 v10, v12
	v_mov_b32_e32 v11, v12

; #define LAS __attribute__((address_space(3)))
; __device__ void boxfilter_unit(const Params& p, LAS unsigned char* lds, int u) {
;     ...
;     for (int i = 0; i < 4; ++i) { const int tok = tid + 512 * i; const int r = tok >> 6, c = tok & 63; const int lo = max(r - hw, 0), hi = min(r + hw, 32);
;         f32x4 s0 = (f32x4){0.f, 0.f, 0.f, 0.f}, s1 = s0;
;         for (int rr = lo; rr < hi; ++rr) { s0 += *(const LAS f32x4*)(X + (rr * 64 + c) * 8); s1 += *(const LAS f32x4*)(X + (rr * 64 + c) * 8 + 4); }
;         const float cnt = (float)(hi - lo);
;         *(LAS f32x4*)(Y + tok * 8) = s0 / cnt; *(LAS f32x4*)(Y + tok * 8 + 4) = s1 / cnt; }
.LBB0_414:
	s_or_b64 exec, exec, s[0:1]
	v_sub_u32_e32 v21, v22, v21
	v_cvt_f32_i32_e32 v21, v21
	v_rcp_f32_e32 v106, v21
	s_nop 0
	v_fma_f32 v107, -v21, v106, 1.0
	v_fmac_f32_e32 v106, v107, v106
	v_fma_f32 v107, -v21, v106, 1.0
	v_fmac_f32_e32 v106, v107, v106
	v_mul_f32_e32 v108, v15, v106
	v_fma_f32 v107, -v21, v108, v15
	v_fma_f32 v15, v107, v106, v108
	v_mul_f32_e32 v108, v14, v106
	v_fma_f32 v107, -v21, v108, v14
	v_fma_f32 v14, v107, v106, v108
	v_mul_f32_e32 v108, v13, v106
	v_fma_f32 v107, -v21, v108, v13
	v_fma_f32 v13, v107, v106, v108
	v_mul_f32_e32 v108, v12, v106
	v_fma_f32 v107, -v21, v108, v12
	v_fma_f32 v12, v107, v106, v108
	v_add_u32_e32 v22, 0x10000, v17
	ds_write_b128 v22, v[12:15]
	v_mul_f32_e32 v108, v11, v106
	v_fma_f32 v107, -v21, v108, v11
	v_fma_f32 v11, v107, v106, v108
	v_mul_f32_e32 v108, v10, v106
	v_fma_f32 v107, -v21, v108, v10
	v_fma_f32 v10, v107, v106, v108
	v_mul_f32_e32 v108, v9, v106
	v_fma_f32 v107, -v21, v108, v9
	v_fma_f32 v9, v107, v106, v108
	v_mul_f32_e32 v108, v8, v106
	v_fma_f32 v107, -v21, v108, v8
	v_fma_f32 v8, v107, v106, v108
	ds_write_b128 v22, v[8:11] offset:16
	v_ashrrev_i32_e32 v8, 6, v0
	v_subrev_u32_e32 v9, s6, v8
	v_add_u32_e32 v8, s6, v8
	v_max_i32_e32 v21, 0, v9
	v_min_i32_e32 v22, 32, v8
	v_mov_b32_e32 v15, 0
	v_cmp_gt_i32_e32 vcc, v22, v21
	v_mov_b32_e32 v14, v15
	v_mov_b32_e32 v13, v15
	v_mov_b32_e32 v12, v15
	v_mov_b32_e32 v11, v15
	v_mov_b32_e32 v10, v15
	v_mov_b32_e32 v9, v15
	v_mov_b32_e32 v8, v15
	s_and_saveexec_b64 s[0:1], vcc
	s_cbranch_execz .LBB0_418
	v_lshlrev_b32_e32 v8, 5, v20
	v_lshl_or_b32 v8, v21, 11, v8
	v_mov_b32_e32 v12, 0
	v_add_u32_e32 v23, 0, v8
	s_mov_b64 s[4:5], 0
	v_mov_b32_e32 v24, v21
	v_mov_b32_e32 v13, v12
	v_mov_b32_e32 v14, v12
	v_mov_b32_e32 v15, v12
	v_mov_b32_e32 v8, v12
	v_mov_b32_e32 v9, v12
	v_mov_b32_e32 v10, v12
	v_mov_b32_e32 v11, v12

; #define LAS __attribute__((address_space(3)))
; __device__ void boxfilter_unit(const Params& p, LAS unsigned char* lds, int u) {
;     ...
;     for (int i = 0; i < 4; ++i) { const int tok = tid + 512 * i; const int r = tok >> 6, c = tok & 63; const int lo = max(r - hw, 0), hi = min(r + hw, 32);
;         f32x4 s0 = (f32x4){0.f, 0.f, 0.f, 0.f}, s1 = s0;
;         for (int rr = lo; rr < hi; ++rr) { s0 += *(const LAS f32x4*)(X + (rr * 64 + c) * 8); s1 += *(const LAS f32x4*)(X + (rr * 64 + c) * 8 + 4); }
;         const float cnt = (float)(hi - lo);
;         *(LAS f32x4*)(Y + tok * 8) = s0 / cnt; *(LAS f32x4*)(Y + tok * 8 + 4) = s1 / cnt; }
;     __syncthreads();
;     for (int i = 0; i < 4; ++i) { const int tok = tid + 512 * i; const int r = tok >> 6, c = tok & 63; const int lo = max(c - hw, 0), hi = min(c + hw, 64);
.LBB0_418:
	s_or_b64 exec, exec, s[0:1]
	v_sub_u32_e32 v21, v22, v21
	v_cvt_f32_i32_e32 v21, v21
	v_rcp_f32_e32 v106, v21
	s_nop 0
	v_fma_f32 v107, -v21, v106, 1.0
	v_fmac_f32_e32 v106, v107, v106
	v_fma_f32 v107, -v21, v106, 1.0
	v_fmac_f32_e32 v106, v107, v106
	v_mul_f32_e32 v108, v15, v106
	v_fma_f32 v107, -v21, v108, v15
	v_fma_f32 v15, v107, v106, v108
	v_mul_f32_e32 v108, v14, v106
	v_fma_f32 v107, -v21, v108, v14
	v_fma_f32 v14, v107, v106, v108
	v_mul_f32_e32 v108, v13, v106
	v_fma_f32 v107, -v21, v108, v13
	v_fma_f32 v13, v107, v106, v108
	v_mul_f32_e32 v108, v12, v106
	v_fma_f32 v107, -v21, v108, v12
	v_fma_f32 v12, v107, v106, v108
	v_add_u32_e32 v22, 0x10000, v16
	ds_write_b128 v22, v[12:15]
	v_mul_f32_e32 v108, v11, v106
	v_fma_f32 v107, -v21, v108, v11
	v_fma_f32 v11, v107, v106, v108
	v_mul_f32_e32 v108, v10, v106
	v_fma_f32 v107, -v21, v108, v10
	v_fma_f32 v10, v107, v106, v108
	v_mul_f32_e32 v108, v9, v106
	v_fma_f32 v107, -v21, v108, v9
	v_fma_f32 v9, v107, v106, v108
	v_mul_f32_e32 v108, v8, v106
	v_fma_f32 v107, -v21, v108, v8
	v_fma_f32 v8, v107, v106, v108
	ds_write_b128 v22, v[8:11] offset:16
	v_subrev_u32_e32 v8, s6, v20
	v_add_u32_e32 v9, s6, v20
	v_max_i32_e32 v21, 0, v8
	v_min_u32_e32 v22, 64, v9
	v_mov_b32_e32 v9, 0
	v_cmp_lt_i32_e64 s[0:1], v8, v22
	v_lshlrev_b32_e32 v23, 5, v21
	v_mov_b32_e32 v8, v9
	v_mov_b32_e32 v11, v9
	v_mov_b32_e32 v10, v9
	v_mov_b32_e32 v13, v9
	v_mov_b32_e32 v12, v9
	v_mov_b32_e32 v15, v9
	v_mov_b32_e32 v14, v9
	s_waitcnt lgkmcnt(0)
	s_barrier
	s_and_saveexec_b64 s[4:5], s[0:1]
	s_cbranch_execz .LBB0_422
	v_lshlrev_b32_e32 v8, 5, v6
	v_and_b32_e32 v8, 0xfffff800, v8
	v_add3_u32 v8, v8, v23, 0
	v_mov_b32_e32 v10, 0
	v_add_u32_e32 v20, 0x10010, v8
	s_mov_b64 s[6:7], 0
	v_mov_b32_e32 v24, v21
	v_mov_b32_e32 v11, v10
	v_mov_b32_e32 v8, v10
	v_mov_b32_e32 v9, v10
	v_mov_b32_e32 v14, v10
	v_mov_b32_e32 v15, v10
	v_mov_b32_e32 v12, v10
	v_mov_b32_e32 v13, v10

; #define LAS __attribute__((address_space(3)))
; __device__ __forceinline__ unsigned cvt_pk_bf16(float lo, float hi) { unsigned r; asm volatile("v_cvt_pk_bf16_f32 %0, %1, %2" : "=v"(r) : "v"(lo), "v"(hi)); return r; }
; __device__ void boxfilter_unit(const Params& p, LAS unsigned char* lds, int u) {
;     ...
;     for (int i = 0; i < 4; ++i) { const int tok = tid + 512 * i; const int r = tok >> 6, c = tok & 63; const int lo = max(c - hw, 0), hi = min(c + hw, 64);
;         f32x4 s0 = (f32x4){0.f, 0.f, 0.f, 0.f}, s1 = s0;
;         for (int cc = lo; cc < hi; ++cc) { s0 += *(const LAS f32x4*)(Y + (r * 64 + cc) * 8); s1 += *(const LAS f32x4*)(Y + (r * 64 + cc) * 8 + 4); }
;         const float cnt = (float)(hi - lo);
;         const f32x4 m0 = s0 / cnt - *(const LAS f32x4*)(X + tok * 8), m1 = s1 / cnt - *(const LAS f32x4*)(X + tok * 8 + 4);
;         u32x4 w; w.x = cvt_pk_bf16(m0[0], m0[1]); w.y = cvt_pk_bf16(m0[2], m0[3]); w.z = cvt_pk_bf16(m1[0], m1[1]); w.w = cvt_pk_bf16(m1[2], m1[3]);
;         *(u32x4*)(dst + (size_t)tok * 512) = w; }
.LBB0_422:
	s_or_b64 exec, exec, s[4:5]
	s_lshl_b32 s4, s2, 5
	s_and_b32 s4, s4, 0xfffff800
	s_ashr_i32 s5, s4, 31
	s_lshl_b64 s[4:5], s[4:5], 10
	s_add_u32 s41, s70, 0xac00000
	v_sub_u32_e32 v20, v22, v21
	s_addc_u32 s94, s71, 0
	v_cvt_f32_i32_e32 v20, v20
	v_rcp_f32_e32 v105, v20
	s_nop 0
	v_fma_f32 v107, -v20, v105, 1.0
	v_fmac_f32_e32 v105, v107, v105
	v_fma_f32 v107, -v20, v105, 1.0
	v_fmac_f32_e32 v105, v107, v105
	s_add_u32 s4, s41, s4
	s_addc_u32 s5, s94, s5
	s_lshl_b32 s6, s9, 8
	s_add_u32 s6, s4, s6
	s_addc_u32 s7, s5, 0
	s_lshl_b32 s4, s8, 4
	s_add_u32 s4, s6, s4
	s_addc_u32 s5, s7, 0
	v_mul_f32_e32 v108, v15, v105
	v_fma_f32 v107, -v20, v108, v15
	v_fma_f32 v29, v107, v105, v108
	v_lshlrev_b64 v[6:7], 10, v[6:7]
	v_mul_f32_e32 v108, v14, v105
	v_fma_f32 v107, -v20, v108, v14
	v_fma_f32 v28, v107, v105, v108
	v_lshl_add_u64 v[6:7], s[4:5], 0, v[6:7]
	v_mul_f32_e32 v108, v13, v105
	v_fma_f32 v107, -v20, v108, v13
	v_fma_f32 v31, v107, v105, v108
	ds_read_b128 v[24:27], v19
	v_mul_f32_e32 v108, v12, v105
	v_fma_f32 v107, -v20, v108, v12
	v_fma_f32 v30, v107, v105, v108
	ds_read_b128 v[12:15], v19 offset:16
	s_waitcnt lgkmcnt(1)
	v_sub_f32_e32 v19, v30, v26
	v_sub_f32_e32 v24, v28, v24
	v_sub_f32_e32 v25, v29, v25
	v_sub_f32_e32 v27, v31, v27
	v_mul_f32_e32 v108, v11, v105
	v_fma_f32 v107, -v20, v108, v11
	v_fma_f32 v11, v107, v105, v108
	s_waitcnt lgkmcnt(0)
	v_sub_f32_e32 v11, v11, v13
	v_mul_f32_e32 v108, v10, v105
	v_fma_f32 v107, -v20, v108, v10
	v_fma_f32 v10, v107, v105, v108
	v_sub_f32_e32 v10, v10, v12
	v_mul_f32_e32 v108, v9, v105
	v_fma_f32 v107, -v20, v108, v9
	v_fma_f32 v9, v107, v105, v108
	v_sub_f32_e32 v15, v9, v15
	v_mul_f32_e32 v108, v8, v105
	v_fma_f32 v107, -v20, v108, v8
	v_fma_f32 v8, v107, v105, v108
	v_sub_f32_e32 v14, v8, v14
	v_cvt_pk_bf16_f32 v8, v24, v25
	v_cvt_pk_bf16_f32 v9, v19, v27
	v_cvt_pk_bf16_f32 v10, v10, v11
	v_cvt_pk_bf16_f32 v11, v14, v15
	global_store_dwordx4 v[6:7], v[8:11], off
	v_mov_b32_e32 v7, 0
	v_mov_b32_e32 v6, v7
	v_mov_b32_e32 v9, v7
	v_mov_b32_e32 v8, v7
	v_mov_b32_e32 v11, v7
	v_mov_b32_e32 v10, v7
	v_mov_b32_e32 v13, v7
	v_mov_b32_e32 v12, v7
	s_and_saveexec_b64 s[6:7], s[0:1]
	s_cbranch_execz .LBB0_426
	v_lshlrev_b32_e32 v6, 5, v4
	v_and_b32_e32 v6, 0xfffff800, v6
	v_add3_u32 v6, v6, v23, 0
	v_mov_b32_e32 v8, 0
	v_add_u32_e32 v14, 0x10010, v6
	s_mov_b64 s[8:9], 0
	v_mov_b32_e32 v15, v21
	v_mov_b32_e32 v9, v8
	v_mov_b32_e32 v6, v8
	v_mov_b32_e32 v7, v8
	v_mov_b32_e32 v12, v8
	v_mov_b32_e32 v13, v8
	v_mov_b32_e32 v10, v8
	v_mov_b32_e32 v11, v8

; #define LAS __attribute__((address_space(3)))
; __device__ __forceinline__ unsigned cvt_pk_bf16(float lo, float hi) { unsigned r; asm volatile("v_cvt_pk_bf16_f32 %0, %1, %2" : "=v"(r) : "v"(lo), "v"(hi)); return r; }
; __device__ void boxfilter_unit(const Params& p, LAS unsigned char* lds, int u) {
;     ...
;     for (int i = 0; i < 4; ++i) { const int tok = tid + 512 * i; const int r = tok >> 6, c = tok & 63; const int lo = max(c - hw, 0), hi = min(c + hw, 64);
;         f32x4 s0 = (f32x4){0.f, 0.f, 0.f, 0.f}, s1 = s0;
;         for (int cc = lo; cc < hi; ++cc) { s0 += *(const LAS f32x4*)(Y + (r * 64 + cc) * 8); s1 += *(const LAS f32x4*)(Y + (r * 64 + cc) * 8 + 4); }
;         const float cnt = (float)(hi - lo);
;         const f32x4 m0 = s0 / cnt - *(const LAS f32x4*)(X + tok * 8), m1 = s1 / cnt - *(const LAS f32x4*)(X + tok * 8 + 4);
;         u32x4 w; w.x = cvt_pk_bf16(m0[0], m0[1]); w.y = cvt_pk_bf16(m0[2], m0[3]); w.z = cvt_pk_bf16(m1[0], m1[1]); w.w = cvt_pk_bf16(m1[2], m1[3]);
;         *(u32x4*)(dst + (size_t)tok * 512) = w; }
.LBB0_426:
	s_or_b64 exec, exec, s[6:7]
	v_lshlrev_b64 v[4:5], 10, v[4:5]
	v_mul_f32_e32 v108, v13, v105
	v_fma_f32 v107, -v20, v108, v13
	v_fma_f32 v28, v107, v105, v108
	v_lshl_add_u64 v[4:5], s[4:5], 0, v[4:5]
	v_mul_f32_e32 v108, v12, v105
	v_fma_f32 v107, -v20, v108, v12
	v_fma_f32 v29, v107, v105, v108
	v_mul_f32_e32 v108, v11, v105
	v_fma_f32 v107, -v20, v108, v11
	v_fma_f32 v11, v107, v105, v108
	ds_read_b128 v[12:15], v18
	v_mul_f32_e32 v108, v10, v105
	v_fma_f32 v107, -v20, v108, v10
	v_fma_f32 v10, v107, v105, v108
	ds_read_b128 v[24:27], v18 offset:16
	s_waitcnt lgkmcnt(1)
	v_sub_f32_e32 v10, v10, v14
	v_sub_f32_e32 v11, v11, v15
	v_sub_f32_e32 v13, v28, v13
	v_sub_f32_e32 v12, v29, v12
	v_mul_f32_e32 v108, v9, v105
	v_fma_f32 v107, -v20, v108, v9
	v_fma_f32 v9, v107, v105, v108
	s_waitcnt lgkmcnt(0)
	v_sub_f32_e32 v9, v9, v25
	v_mul_f32_e32 v108, v8, v105
	v_fma_f32 v107, -v20, v108, v8
	v_fma_f32 v8, v107, v105, v108
	v_sub_f32_e32 v8, v8, v24
	v_mul_f32_e32 v108, v7, v105
	v_fma_f32 v107, -v20, v108, v7
	v_fma_f32 v7, v107, v105, v108
	v_mul_f32_e32 v108, v6, v105
	v_fma_f32 v107, -v20, v108, v6
	v_fma_f32 v6, v107, v105, v108
	v_sub_f32_e32 v14, v6, v26
	v_sub_f32_e32 v15, v7, v27
	v_cvt_pk_bf16_f32 v6, v12, v13
	v_cvt_pk_bf16_f32 v7, v10, v11
	v_cvt_pk_bf16_f32 v8, v8, v9
	v_cvt_pk_bf16_f32 v9, v14, v15
	global_store_dwordx4 v[4:5], v[6:9], off
	v_mov_b32_e32 v5, 0
	v_mov_b32_e32 v4, v5
	v_mov_b32_e32 v7, v5
	v_mov_b32_e32 v6, v5
	v_mov_b32_e32 v9, v5
	v_mov_b32_e32 v8, v5
	v_mov_b32_e32 v11, v5
	v_mov_b32_e32 v10, v5
	s_and_saveexec_b64 s[6:7], s[0:1]
	s_cbranch_execz .LBB0_430
	v_lshlrev_b32_e32 v4, 5, v2
	v_and_b32_e32 v4, 0xfffff800, v4
	v_add3_u32 v4, v4, v23, 0
	v_mov_b32_e32 v6, 0
	v_add_u32_e32 v12, 0x10010, v4
	s_mov_b64 s[8:9], 0
	v_mov_b32_e32 v13, v21
	v_mov_b32_e32 v7, v6
	v_mov_b32_e32 v4, v6
	v_mov_b32_e32 v5, v6
	v_mov_b32_e32 v10, v6
	v_mov_b32_e32 v11, v6
	v_mov_b32_e32 v8, v6
	v_mov_b32_e32 v9, v6

; #define LAS __attribute__((address_space(3)))
; __device__ __forceinline__ unsigned cvt_pk_bf16(float lo, float hi) { unsigned r; asm volatile("v_cvt_pk_bf16_f32 %0, %1, %2" : "=v"(r) : "v"(lo), "v"(hi)); return r; }
; __device__ void boxfilter_unit(const Params& p, LAS unsigned char* lds, int u) {
;     ...
;     for (int i = 0; i < 4; ++i) { const int tok = tid + 512 * i; const int r = tok >> 6, c = tok & 63; const int lo = max(c - hw, 0), hi = min(c + hw, 64);
;         f32x4 s0 = (f32x4){0.f, 0.f, 0.f, 0.f}, s1 = s0;
;         for (int cc = lo; cc < hi; ++cc) { s0 += *(const LAS f32x4*)(Y + (r * 64 + cc) * 8); s1 += *(const LAS f32x4*)(Y + (r * 64 + cc) * 8 + 4); }
;         const float cnt = (float)(hi - lo);
;         const f32x4 m0 = s0 / cnt - *(const LAS f32x4*)(X + tok * 8), m1 = s1 / cnt - *(const LAS f32x4*)(X + tok * 8 + 4);
;         u32x4 w; w.x = cvt_pk_bf16(m0[0], m0[1]); w.y = cvt_pk_bf16(m0[2], m0[3]); w.z = cvt_pk_bf16(m1[0], m1[1]); w.w = cvt_pk_bf16(m1[2], m1[3]);
;         *(u32x4*)(dst + (size_t)tok * 512) = w; }
.LBB0_430:
	s_or_b64 exec, exec, s[6:7]
	v_lshlrev_b64 v[2:3], 10, v[2:3]
	v_mul_f32_e32 v108, v11, v105
	v_fma_f32 v107, -v20, v108, v11
	v_fma_f32 v15, v107, v105, v108
	v_lshl_add_u64 v[2:3], s[4:5], 0, v[2:3]
	v_mul_f32_e32 v108, v10, v105
	v_fma_f32 v107, -v20, v108, v10
	v_fma_f32 v18, v107, v105, v108
	v_mul_f32_e32 v108, v9, v105
	v_fma_f32 v107, -v20, v108, v9
	v_fma_f32 v9, v107, v105, v108
	ds_read_b128 v[10:13], v17
	v_mul_f32_e32 v108, v8, v105
	v_fma_f32 v107, -v20, v108, v8
	v_fma_f32 v8, v107, v105, v108
	ds_read_b128 v[24:27], v17 offset:16
	s_waitcnt lgkmcnt(1)
	v_sub_f32_e32 v8, v8, v12
	v_sub_f32_e32 v9, v9, v13
	v_sub_f32_e32 v11, v15, v11
	v_sub_f32_e32 v10, v18, v10
	v_mul_f32_e32 v108, v7, v105
	v_fma_f32 v107, -v20, v108, v7
	v_fma_f32 v7, v107, v105, v108
	s_waitcnt lgkmcnt(0)
	v_sub_f32_e32 v7, v7, v25
	v_mul_f32_e32 v108, v6, v105
	v_fma_f32 v107, -v20, v108, v6
	v_fma_f32 v6, v107, v105, v108
	v_sub_f32_e32 v6, v6, v24
	v_mul_f32_e32 v108, v5, v105
	v_fma_f32 v107, -v20, v108, v5
	v_fma_f32 v5, v107, v105, v108
	v_mul_f32_e32 v108, v4, v105
	v_fma_f32 v107, -v20, v108, v4
	v_fma_f32 v4, v107, v105, v108
	v_sub_f32_e32 v12, v4, v26
	v_sub_f32_e32 v13, v5, v27
	v_cvt_pk_bf16_f32 v4, v10, v11
	v_cvt_pk_bf16_f32 v5, v8, v9
	v_cvt_pk_bf16_f32 v6, v6, v7
	v_cvt_pk_bf16_f32 v7, v12, v13
	global_store_dwordx4 v[2:3], v[4:7], off
	v_mov_b32_e32 v3, 0
	v_mov_b32_e32 v2, v3
	v_mov_b32_e32 v5, v3
	v_mov_b32_e32 v4, v3
	v_mov_b32_e32 v7, v3
	v_mov_b32_e32 v6, v3
	v_mov_b32_e32 v9, v3
	v_mov_b32_e32 v8, v3
	s_and_saveexec_b64 s[6:7], s[0:1]
	s_cbranch_execz .LBB0_434
	v_lshlrev_b32_e32 v2, 5, v0
	v_and_b32_e32 v2, 0xfffff800, v2
	v_add3_u32 v2, v2, v23, 0
	v_mov_b32_e32 v4, 0
	v_add_u32_e32 v10, 0x10010, v2
	s_mov_b64 s[0:1], 0
	v_mov_b32_e32 v5, v4
	v_mov_b32_e32 v2, v4
	v_mov_b32_e32 v3, v4
	v_mov_b32_e32 v8, v4
	v_mov_b32_e32 v9, v4
	v_mov_b32_e32 v6, v4
	v_mov_b32_e32 v7, v4

; #define LAS __attribute__((address_space(3)))
; __device__ __forceinline__ float bf_lo(unsigned w) { return __uint_as_float(w << 16); }
; __device__ __forceinline__ float bf_hi(unsigned w) { return __uint_as_float(w & 0xffff0000u); }
; __device__ __forceinline__ unsigned cvt_pk_bf16(float lo, float hi) { unsigned r; asm volatile("v_cvt_pk_bf16_f32 %0, %1, %2" : "=v"(r) : "v"(lo), "v"(hi)); return r; }
; __device__ void boxfilter_unit(const Params& p, LAS unsigned char* lds, int u) {
;     ...
;     const bf16_t* src = (const bf16_t*)(p.ws + OFF_P) + (size_t)(b * 64 + g * 16 + cb) * 2048 * 8;
;     bf16_t* dst = (bf16_t*)(p.ws + OFF_MX) + (size_t)(b * 2048) * 512 + g * 128 + cb * 8;
; #pragma unroll
;     for (int i = 0; i < 4; ++i) { const int tok = tid + 512 * i; const u32x4 v = __builtin_nontemporal_load((const u32x4*)(src + (size_t)tok * 8));
;         *(LAS f32x4*)(X + tok * 8) = (f32x4){bf_lo(v.x), bf_hi(v.x), bf_lo(v.y), bf_hi(v.y)}; *(LAS f32x4*)(X + tok * 8 + 4) = (f32x4){bf_lo(v.z), bf_hi(v.z), bf_lo(v.w), bf_hi(v.w)}; }
;     ...
;     for (int i = 0; i < 4; ++i) { const int tok = tid + 512 * i; const int r = tok >> 6, c = tok & 63; const int lo = max(c - hw, 0), hi = min(c + hw, 64);
;         f32x4 s0 = (f32x4){0.f, 0.f, 0.f, 0.f}, s1 = s0;
;         for (int cc = lo; cc < hi; ++cc) { s0 += *(const LAS f32x4*)(Y + (r * 64 + cc) * 8); s1 += *(const LAS f32x4*)(Y + (r * 64 + cc) * 8 + 4); }
;         const float cnt = (float)(hi - lo);
;         const f32x4 m0 = s0 / cnt - *(const LAS f32x4*)(X + tok * 8), m1 = s1 / cnt - *(const LAS f32x4*)(X + tok * 8 + 4);
;         u32x4 w; w.x = cvt_pk_bf16(m0[0], m0[1]); w.y = cvt_pk_bf16(m0[2], m0[3]); w.z = cvt_pk_bf16(m1[0], m1[1]); w.w = cvt_pk_bf16(m1[2], m1[3]);
;         *(u32x4*)(dst + (size_t)tok * 512) = w; }
.LBB0_434:
	s_or_b64 exec, exec, s[6:7]
	s_sub_i32 s9, s34, s3
	v_mul_f32_e32 v108, v9, v105
	v_fma_f32 v107, -v20, v108, v9
	v_fma_f32 v17, v107, v105, v108
	s_addk_i32 s9, 0x1fc
	v_mul_f32_e32 v108, v8, v105
	v_fma_f32 v107, -v20, v108, v8
	v_fma_f32 v18, v107, v105, v108
	s_bfe_u32 s8, s9, 0x20004
	v_mul_f32_e32 v108, v7, v105
	v_fma_f32 v107, -v20, v108, v7
	v_fma_f32 v7, v107, v105, v108
	ds_read_b128 v[8:11], v16
	v_mul_f32_e32 v108, v6, v105
	v_fma_f32 v107, -v20, v108, v6
	v_fma_f32 v6, v107, v105, v108
	ds_read_b128 v[12:15], v16 offset:16
	s_and_b32 s3, s9, 15
	s_waitcnt lgkmcnt(1)
	v_sub_f32_e32 v6, v6, v10
	v_sub_f32_e32 v7, v7, v11
	v_sub_f32_e32 v9, v17, v9
	v_sub_f32_e32 v8, v18, v8
	v_mul_f32_e32 v108, v5, v105
	v_fma_f32 v107, -v20, v108, v5
	v_fma_f32 v5, v107, v105, v108
	v_lshlrev_b64 v[0:1], 10, v[0:1]
	v_mul_f32_e32 v108, v4, v105
	v_fma_f32 v107, -v20, v108, v4
	v_fma_f32 v4, v107, v105, v108
	s_waitcnt lgkmcnt(0)
	v_sub_f32_e32 v4, v4, v12
	v_mul_f32_e32 v108, v3, v105
	v_fma_f32 v107, -v20, v108, v3
	v_fma_f32 v3, v107, v105, v108
	s_and_b32 s0, s9, 0xffffffc0
	s_lshl_b32 s1, s8, 4
	s_or_b32 s0, s1, s0
	s_or_b32 s0, s0, s3
	s_ashr_i32 s1, s0, 31
	v_mul_f32_e32 v108, v2, v105
	v_fma_f32 v107, -v20, v108, v2
	v_fma_f32 v2, v107, v105, v108
	s_lshl_b64 s[0:1], s[0:1], 15
	v_sub_f32_e32 v10, v2, v14
	v_sub_f32_e32 v11, v3, v15
	v_sub_f32_e32 v5, v5, v13
	v_cvt_pk_bf16_f32 v2, v8, v9
	v_cvt_pk_bf16_f32 v3, v6, v7
	v_lshl_add_u64 v[0:1], s[4:5], 0, v[0:1]
	v_mov_b32_e32 v6, v224
	s_add_u32 s0, s44, s0
	v_cvt_pk_bf16_f32 v4, v4, v5
	v_cvt_pk_bf16_f32 v5, v10, v11
	global_store_dwordx4 v[0:1], v[2:5], off
	s_barrier
	s_addc_u32 s1, s45, s1
	v_ashrrev_i32_e32 v7, 31, v6
	v_lshl_add_u64 v[0:1], v[6:7], 4, s[0:1]
	v_add_u32_e32 v4, 0x200, v6
	global_load_dwordx4 v[8:11], v[0:1], off nt
	v_ashrrev_i32_e32 v5, 31, v4
	v_lshl_add_u64 v[0:1], v[4:5], 4, s[0:1]
	v_add_u32_e32 v2, 0x400, v6
	global_load_dwordx4 v[12:15], v[0:1], off nt
	v_ashrrev_i32_e32 v3, 31, v2
	v_lshl_add_u64 v[0:1], v[2:3], 4, s[0:1]
	global_load_dwordx4 v[20:23], v[0:1], off nt
	v_add_u32_e32 v0, 0x600, v6
	v_ashrrev_i32_e32 v1, 31, v0
	v_lshl_add_u64 v[16:17], v[0:1], 4, s[0:1]
	global_load_dwordx4 v[24:27], v[16:17], off nt
	s_lshl_b32 s6, 1, s8
	s_waitcnt vmcnt(3)
	v_lshlrev_b32_e32 v28, 16, v8
	v_and_b32_e32 v29, 0xffff0000, v8
	v_lshlrev_b32_e32 v8, 5, v6
	v_lshlrev_b32_e32 v30, 16, v9
	v_and_b32_e32 v31, 0xffff0000, v9
	v_add_u32_e32 v19, 0, v8
	v_lshlrev_b32_e32 v8, 16, v10
	v_and_b32_e32 v9, 0xffff0000, v10
	v_lshlrev_b32_e32 v10, 16, v11
	v_and_b32_e32 v11, 0xffff0000, v11
	ds_write_b128 v19, v[8:11] offset:16
	s_waitcnt vmcnt(2)
	v_lshlrev_b32_e32 v8, 16, v12
	v_and_b32_e32 v9, 0xffff0000, v12
	v_lshlrev_b32_e32 v12, 5, v4
	v_lshlrev_b32_e32 v10, 16, v13
	v_and_b32_e32 v11, 0xffff0000, v13
	v_add_u32_e32 v18, 0, v12
	ds_write_b128 v18, v[8:11]
	v_lshlrev_b32_e32 v8, 16, v14
	v_and_b32_e32 v9, 0xffff0000, v14
	v_lshlrev_b32_e32 v10, 16, v15
	v_and_b32_e32 v11, 0xffff0000, v15
	v_lshlrev_b32_e32 v12, 5, v2
	ds_write_b128 v18, v[8:11] offset:16
	s_waitcnt vmcnt(1)
	v_lshlrev_b32_e32 v8, 16, v20
	v_and_b32_e32 v9, 0xffff0000, v20
	v_lshlrev_b32_e32 v10, 16, v21
	v_and_b32_e32 v11, 0xffff0000, v21
	v_add_u32_e32 v17, 0, v12
	ds_write_b128 v17, v[8:11]
	v_lshlrev_b32_e32 v8, 16, v22
	v_and_b32_e32 v9, 0xffff0000, v22
	v_lshlrev_b32_e32 v10, 16, v23
	v_and_b32_e32 v11, 0xffff0000, v23
	v_lshlrev_b32_e32 v12, 5, v0
	ds_write_b128 v17, v[8:11] offset:16
	s_waitcnt vmcnt(0)
	v_lshlrev_b32_e32 v8, 16, v24
	v_and_b32_e32 v9, 0xffff0000, v24
	v_lshlrev_b32_e32 v10, 16, v25
	v_and_b32_e32 v11, 0xffff0000, v25
	v_add_u32_e32 v16, 0, v12
	ds_write_b128 v16, v[8:11]
	v_lshlrev_b32_e32 v8, 16, v26
	v_and_b32_e32 v9, 0xffff0000, v26
	v_lshlrev_b32_e32 v10, 16, v27
	v_and_b32_e32 v11, 0xffff0000, v27
	ds_write_b128 v16, v[8:11] offset:16
	v_ashrrev_i32_e32 v8, 6, v6
	v_subrev_u32_e32 v9, s6, v8
	v_add_u32_e32 v8, s6, v8
	v_max_i32_e32 v21, 0, v9
	v_min_i32_e32 v22, 32, v8
	v_mov_b32_e32 v15, 0
	v_cmp_gt_i32_e32 vcc, v22, v21
	v_and_b32_e32 v20, 63, v6
	v_mov_b32_e32 v14, v15
	v_mov_b32_e32 v13, v15
	v_mov_b32_e32 v12, v15
	v_mov_b32_e32 v11, v15
	v_mov_b32_e32 v10, v15
	v_mov_b32_e32 v9, v15
	v_mov_b32_e32 v8, v15
	ds_write_b128 v19, v[28:31]
	s_waitcnt lgkmcnt(0)
	s_barrier
	s_and_saveexec_b64 s[0:1], vcc
	s_cbranch_execz .LBB0_438
	v_lshlrev_b32_e32 v8, 5, v20
	v_lshl_or_b32 v8, v21, 11, v8
	v_mov_b32_e32 v12, 0
	v_add_u32_e32 v23, 0, v8
	s_mov_b64 s[4:5], 0
	v_mov_b32_e32 v24, v21
	v_mov_b32_e32 v13, v12
	v_mov_b32_e32 v14, v12
	v_mov_b32_e32 v15, v12
	v_mov_b32_e32 v8, v12
	v_mov_b32_e32 v9, v12
	v_mov_b32_e32 v10, v12
	v_mov_b32_e32 v11, v12

; #define LAS __attribute__((address_space(3)))
; __device__ void boxfilter_unit(const Params& p, LAS unsigned char* lds, int u) {
;     ...
;     for (int i = 0; i < 4; ++i) { const int tok = tid + 512 * i; const int r = tok >> 6, c = tok & 63; const int lo = max(r - hw, 0), hi = min(r + hw, 32);
;         f32x4 s0 = (f32x4){0.f, 0.f, 0.f, 0.f}, s1 = s0;
;         for (int rr = lo; rr < hi; ++rr) { s0 += *(const LAS f32x4*)(X + (rr * 64 + c) * 8); s1 += *(const LAS f32x4*)(X + (rr * 64 + c) * 8 + 4); }
;         const float cnt = (float)(hi - lo);
;         *(LAS f32x4*)(Y + tok * 8) = s0 / cnt; *(LAS f32x4*)(Y + tok * 8 + 4) = s1 / cnt; }
.LBB0_438:
	s_or_b64 exec, exec, s[0:1]
	v_sub_u32_e32 v21, v22, v21
	v_cvt_f32_i32_e32 v21, v21
	v_rcp_f32_e32 v106, v21
	s_nop 0
	v_fma_f32 v107, -v21, v106, 1.0
	v_fmac_f32_e32 v106, v107, v106
	v_fma_f32 v107, -v21, v106, 1.0
	v_fmac_f32_e32 v106, v107, v106
	v_mul_f32_e32 v108, v15, v106
	v_fma_f32 v107, -v21, v108, v15
	v_fma_f32 v15, v107, v106, v108
	v_mul_f32_e32 v108, v14, v106
	v_fma_f32 v107, -v21, v108, v14
	v_fma_f32 v14, v107, v106, v108
	v_mul_f32_e32 v108, v13, v106
	v_fma_f32 v107, -v21, v108, v13
	v_fma_f32 v13, v107, v106, v108
	v_mul_f32_e32 v108, v12, v106
	v_fma_f32 v107, -v21, v108, v12
	v_fma_f32 v12, v107, v106, v108
	v_add_u32_e32 v22, 0x10000, v19
	ds_write_b128 v22, v[12:15]
	v_mul_f32_e32 v108, v11, v106
	v_fma_f32 v107, -v21, v108, v11
	v_fma_f32 v11, v107, v106, v108
	v_mul_f32_e32 v108, v10, v106
	v_fma_f32 v107, -v21, v108, v10
	v_fma_f32 v10, v107, v106, v108
	v_mul_f32_e32 v108, v9, v106
	v_fma_f32 v107, -v21, v108, v9
	v_fma_f32 v9, v107, v106, v108
	v_mul_f32_e32 v108, v8, v106
	v_fma_f32 v107, -v21, v108, v8
	v_fma_f32 v8, v107, v106, v108
	ds_write_b128 v22, v[8:11] offset:16
	v_ashrrev_i32_e32 v8, 6, v4
	v_subrev_u32_e32 v9, s6, v8
	v_add_u32_e32 v8, s6, v8
	v_max_i32_e32 v21, 0, v9
	v_min_i32_e32 v22, 32, v8
	v_mov_b32_e32 v15, 0
	v_cmp_gt_i32_e32 vcc, v22, v21
	v_mov_b32_e32 v14, v15
	v_mov_b32_e32 v13, v15
	v_mov_b32_e32 v12, v15
	v_mov_b32_e32 v11, v15
	v_mov_b32_e32 v10, v15
	v_mov_b32_e32 v9, v15
	v_mov_b32_e32 v8, v15
	s_and_saveexec_b64 s[0:1], vcc
	s_cbranch_execz .LBB0_442
	v_lshlrev_b32_e32 v8, 5, v20
	v_lshl_or_b32 v8, v21, 11, v8
	v_mov_b32_e32 v12, 0
	v_add_u32_e32 v23, 0, v8
	s_mov_b64 s[4:5], 0
	v_mov_b32_e32 v24, v21
	v_mov_b32_e32 v13, v12
	v_mov_b32_e32 v14, v12
	v_mov_b32_e32 v15, v12
	v_mov_b32_e32 v8, v12
	v_mov_b32_e32 v9, v12
	v_mov_b32_e32 v10, v12
	v_mov_b32_e32 v11, v12

; #define LAS __attribute__((address_space(3)))
; __device__ __forceinline__ unsigned cvt_pk_bf16(float lo, float hi) { unsigned r; asm volatile("v_cvt_pk_bf16_f32 %0, %1, %2" : "=v"(r) : "v"(lo), "v"(hi)); return r; }
; __device__ void boxfilter_unit(const Params& p, LAS unsigned char* lds, int u) {
;     ...
;     for (int i = 0; i < 4; ++i) { const int tok = tid + 512 * i; const int r = tok >> 6, c = tok & 63; const int lo = max(c - hw, 0), hi = min(c + hw, 64);
;         f32x4 s0 = (f32x4){0.f, 0.f, 0.f, 0.f}, s1 = s0;
;         for (int cc = lo; cc < hi; ++cc) { s0 += *(const LAS f32x4*)(Y + (r * 64 + cc) * 8); s1 += *(const LAS f32x4*)(Y + (r * 64 + cc) * 8 + 4); }
;         const float cnt = (float)(hi - lo);
;         const f32x4 m0 = s0 / cnt - *(const LAS f32x4*)(X + tok * 8), m1 = s1 / cnt - *(const LAS f32x4*)(X + tok * 8 + 4);
;         u32x4 w; w.x = cvt_pk_bf16(m0[0], m0[1]); w.y = cvt_pk_bf16(m0[2], m0[3]); w.z = cvt_pk_bf16(m1[0], m1[1]); w.w = cvt_pk_bf16(m1[2], m1[3]);
;         *(u32x4*)(dst + (size_t)tok * 512) = w; }
.LBB0_454:
	s_or_b64 exec, exec, s[4:5]
	s_lshl_b32 s4, s9, 5
	s_and_b32 s4, s4, 0xfffff800
	s_ashr_i32 s5, s4, 31
	v_sub_u32_e32 v20, v22, v21
	s_lshl_b64 s[4:5], s[4:5], 10
	v_cvt_f32_i32_e32 v20, v20
	v_rcp_f32_e32 v105, v20
	s_nop 0
	v_fma_f32 v107, -v20, v105, 1.0
	v_fmac_f32_e32 v105, v107, v105
	v_fma_f32 v107, -v20, v105, 1.0
	v_fmac_f32_e32 v105, v107, v105
	s_add_u32 s4, s41, s4
	s_addc_u32 s5, s94, s5
	s_lshl_b32 s6, s8, 8
	s_add_u32 s6, s4, s6
	s_addc_u32 s7, s5, 0
	s_lshl_b32 s3, s3, 4
	s_add_u32 s4, s6, s3
	s_addc_u32 s5, s7, 0
	v_mul_f32_e32 v108, v15, v105
	v_fma_f32 v107, -v20, v108, v15
	v_fma_f32 v29, v107, v105, v108
	v_lshlrev_b64 v[6:7], 10, v[6:7]
	v_mul_f32_e32 v108, v14, v105
	v_fma_f32 v107, -v20, v108, v14
	v_fma_f32 v28, v107, v105, v108
	v_lshl_add_u64 v[6:7], s[4:5], 0, v[6:7]
	v_mul_f32_e32 v108, v13, v105
	v_fma_f32 v107, -v20, v108, v13
	v_fma_f32 v31, v107, v105, v108
	ds_read_b128 v[24:27], v19
	v_mul_f32_e32 v108, v12, v105
	v_fma_f32 v107, -v20, v108, v12
	v_fma_f32 v30, v107, v105, v108
	ds_read_b128 v[12:15], v19 offset:16
	s_waitcnt lgkmcnt(1)
	v_sub_f32_e32 v19, v30, v26
	v_sub_f32_e32 v24, v28, v24
	v_sub_f32_e32 v25, v29, v25
	v_sub_f32_e32 v27, v31, v27
	v_mul_f32_e32 v108, v11, v105
	v_fma_f32 v107, -v20, v108, v11
	v_fma_f32 v11, v107, v105, v108
	s_waitcnt lgkmcnt(0)
	v_sub_f32_e32 v11, v11, v13
	v_mul_f32_e32 v108, v10, v105
	v_fma_f32 v107, -v20, v108, v10
	v_fma_f32 v10, v107, v105, v108
	v_sub_f32_e32 v10, v10, v12
	v_mul_f32_e32 v108, v9, v105
	v_fma_f32 v107, -v20, v108, v9
	v_fma_f32 v9, v107, v105, v108
	v_sub_f32_e32 v15, v9, v15
	v_mul_f32_e32 v108, v8, v105
	v_fma_f32 v107, -v20, v108, v8
	v_fma_f32 v8, v107, v105, v108
	v_sub_f32_e32 v14, v8, v14
	v_cvt_pk_bf16_f32 v8, v24, v25
	v_cvt_pk_bf16_f32 v9, v19, v27
	v_cvt_pk_bf16_f32 v10, v10, v11
	v_cvt_pk_bf16_f32 v11, v14, v15
	global_store_dwordx4 v[6:7], v[8:11], off
	v_mov_b32_e32 v7, 0
	v_mov_b32_e32 v6, v7
	v_mov_b32_e32 v9, v7
	v_mov_b32_e32 v8, v7
	v_mov_b32_e32 v11, v7
	v_mov_b32_e32 v10, v7
	v_mov_b32_e32 v13, v7
	v_mov_b32_e32 v12, v7
	s_and_saveexec_b64 s[6:7], s[0:1]
	s_cbranch_execz .LBB0_458
	v_lshlrev_b32_e32 v6, 5, v4
	v_and_b32_e32 v6, 0xfffff800, v6
	v_add3_u32 v6, v6, v23, 0
	v_mov_b32_e32 v8, 0
	v_add_u32_e32 v14, 0x10010, v6
	s_mov_b64 s[8:9], 0
	v_mov_b32_e32 v15, v21
	v_mov_b32_e32 v9, v8
	v_mov_b32_e32 v6, v8
	v_mov_b32_e32 v7, v8
	v_mov_b32_e32 v12, v8
	v_mov_b32_e32 v13, v8
	v_mov_b32_e32 v10, v8
	v_mov_b32_e32 v11, v8

; #define LAS __attribute__((address_space(3)))
; __device__ __forceinline__ unsigned cvt_pk_bf16(float lo, float hi) { unsigned r; asm volatile("v_cvt_pk_bf16_f32 %0, %1, %2" : "=v"(r) : "v"(lo), "v"(hi)); return r; }
; __device__ void boxfilter_unit(const Params& p, LAS unsigned char* lds, int u) {
;     ...
;     for (int i = 0; i < 4; ++i) { const int tok = tid + 512 * i; const int r = tok >> 6, c = tok & 63; const int lo = max(c - hw, 0), hi = min(c + hw, 64);
;         f32x4 s0 = (f32x4){0.f, 0.f, 0.f, 0.f}, s1 = s0;
;         for (int cc = lo; cc < hi; ++cc) { s0 += *(const LAS f32x4*)(Y + (r * 64 + cc) * 8); s1 += *(const LAS f32x4*)(Y + (r * 64 + cc) * 8 + 4); }
;         const float cnt = (float)(hi - lo);
;         const f32x4 m0 = s0 / cnt - *(const LAS f32x4*)(X + tok * 8), m1 = s1 / cnt - *(const LAS f32x4*)(X + tok * 8 + 4);
;         u32x4 w; w.x = cvt_pk_bf16(m0[0], m0[1]); w.y = cvt_pk_bf16(m0[2], m0[3]); w.z = cvt_pk_bf16(m1[0], m1[1]); w.w = cvt_pk_bf16(m1[2], m1[3]);
;         *(u32x4*)(dst + (size_t)tok * 512) = w; }
; __device__ __forceinline__ void run_phase(const Params& p, LAS unsigned char* lds, int ph) {
;     ...
;         for (int idx = blockIdx.x * 512 + tid; idx < 512 * 512; idx += NWG * 512) { const int n = idx >> 9, k = idx & 511; const int gn = n >> 7, gk = k >> 7;
;             const float v = (gn == gk) ? p.pool_w[(size_t)(gn * 128 + (k & 127)) * 128 + (n & 127)] : 0.f;
;             bt[idx] = (bf16_t)(cvt_pk_bf16(v, 0.f) & 0xffffu); }
.LBB0_466:
	s_or_b64 exec, exec, s[6:7]
	v_lshlrev_b64 v[0:1], 10, v[0:1]
	v_mul_f32_e32 v108, v9, v105
	v_fma_f32 v107, -v20, v108, v9
	v_fma_f32 v17, v107, v105, v108
	v_lshl_add_u64 v[0:1], s[4:5], 0, v[0:1]
	v_mul_f32_e32 v108, v8, v105
	v_fma_f32 v107, -v20, v108, v8
	v_fma_f32 v18, v107, v105, v108
	v_mul_f32_e32 v108, v7, v105
	v_fma_f32 v107, -v20, v108, v7
	v_fma_f32 v7, v107, v105, v108
	ds_read_b128 v[8:11], v16
	v_mul_f32_e32 v108, v6, v105
	v_fma_f32 v107, -v20, v108, v6
	v_fma_f32 v6, v107, v105, v108
	ds_read_b128 v[12:15], v16 offset:16
	s_waitcnt lgkmcnt(1)
	v_sub_f32_e32 v6, v6, v10
	v_sub_f32_e32 v7, v7, v11
	v_sub_f32_e32 v9, v17, v9
	v_sub_f32_e32 v8, v18, v8
	v_mul_f32_e32 v108, v5, v105
	v_fma_f32 v107, -v20, v108, v5
	v_fma_f32 v5, v107, v105, v108
	s_waitcnt lgkmcnt(0)
	v_sub_f32_e32 v5, v5, v13
	v_mul_f32_e32 v108, v4, v105
	v_fma_f32 v107, -v20, v108, v4
	v_fma_f32 v4, v107, v105, v108
	v_sub_f32_e32 v4, v4, v12
	v_mul_f32_e32 v108, v3, v105
	v_fma_f32 v107, -v20, v108, v3
	v_fma_f32 v3, v107, v105, v108
	s_mov_b32 s0, 0x40000
	v_mul_f32_e32 v108, v2, v105
	v_fma_f32 v107, -v20, v108, v2
	v_fma_f32 v2, v107, v105, v108
	v_sub_f32_e32 v10, v2, v14
	v_sub_f32_e32 v11, v3, v15
	v_cvt_pk_bf16_f32 v2, v8, v9
	v_cvt_pk_bf16_f32 v3, v6, v7
	v_cvt_pk_bf16_f32 v4, v4, v5
	v_cvt_pk_bf16_f32 v5, v10, v11
	global_store_dwordx4 v[0:1], v[2:5], off
	v_lshl_add_u32 v0, s2, 9, v104
	v_cmp_gt_i32_e32 vcc, s0, v0
	s_barrier
	s_and_saveexec_b64 s[0:1], vcc
	s_cbranch_execz .LBB0_471
	v_ashrrev_i32_e32 v1, 31, v0
	v_lshl_add_u64 v[2:3], v[0:1], 1, s[70:71]
	s_mov_b64 s[4:5], 0x2000000
	v_and_b32_e32 v6, 0x7f, v104
	v_lshl_add_u64 v[2:3], v[2:3], 0, s[4:5]
	s_mov_b64 s[4:5], 0
	v_mov_b32_e32 v5, 0
	s_mov_b64 s[6:7], 0x40000
	s_mov_b32 s3, 0x1ffff
	s_branch .LBB0_469
